# v8 + GEMM9 final f32 output written with nt (streaming) stores: write-once data no longer displaces the A/B panels in L2
# speedup vs baseline: 1.0342x; 1.0005x over previous
;     __device__ __forceinline__ void operator()(const f32x4 (&acc_)[2][2][4][2], const pg8::Unit& u, int wr, int wc, int fr, int fq) const {
;     ...
;         for (int bj = 0; bj < 2; ++bj) { g[bj][0] = *(const f32x4*)(gain + col0 + bj * 128); g[bj][1] = *(const f32x4*)(gain + col0 + bj * 128 + 4); }
; #pragma unroll
;         for (int ai = 0; ai < 2; ++ai)
; #pragma unroll
;             for (int m = 0; m < 4; ++m) {
;                 const int row = row0 + ai * 128 + m * 16; const float* xp = xch + (size_t)row * 16 + 4 * fq;
;                 float s = (__hip_atomic_load(xp + 0, __ATOMIC_RELAXED, __HIP_MEMORY_SCOPE_AGENT) + __hip_atomic_load(xp + 1, __ATOMIC_RELAXED, __HIP_MEMORY_SCOPE_AGENT))
;                         + (__hip_atomic_load(xp + 2, __ATOMIC_RELAXED, __HIP_MEMORY_SCOPE_AGENT) + __hip_atomic_load(xp + 3, __ATOMIC_RELAXED, __HIP_MEMORY_SCOPE_AGENT));
;                 s += __shfl_xor(s, 16); s += __shfl_xor(s, 32);
;                 const float rstd = __builtin_amdgcn_rsqf(s * (1.0f / 1024.0f) + EPS);
; #pragma unroll
;                 for (int bj = 0; bj < 2; ++bj) { const size_t off = (size_t)row * D + col0 + bj * 128;
;                     *(f32x4*)(out + off) = A[ai][bj][m][0] * rstd * g[bj][0]; *(f32x4*)(out + off + 4) = A[ai][bj][m][1] * rstd * g[bj][1]; }
;             }
.LBB0_982:
	v_lshlrev_b64 v[148:149], 2, v[148:149]
	s_waitcnt vmcnt(0)
	v_lshl_add_u64 v[8:9], s[24:25], 0, v[148:149]
	v_lshl_add_u64 v[156:157], v[136:137], 0, v[156:157]
	global_load_dwordx4 v[4:7], v[8:9], off offset:16
	global_load_dwordx4 v[12:15], v[8:9], off
	global_load_dwordx4 v[0:3], v[8:9], off offset:528
	s_nop 0
	global_load_dwordx4 v[8:11], v[8:9], off offset:512
	s_nop 0
	global_load_dwordx4 v[208:211], v[156:157], off sc1
	v_lshlrev_b64 v[146:147], 12, v[146:147]
	v_lshl_add_u64 v[146:147], s[8:9], 0, v[146:147]
	v_lshl_add_u64 v[146:147], v[146:147], 0, v[148:149]
	v_lshl_add_u64 v[160:161], v[136:137], 0, v[160:161]
	global_load_dwordx4 v[214:217], v[160:161], off sc1
	v_lshl_add_u64 v[242:243], v[136:137], 0, v[164:165]
	global_load_dwordx4 v[218:221], v[242:243], off sc1
	v_lshl_add_u64 v[244:245], v[136:137], 0, v[168:169]
	global_load_dwordx4 v[222:225], v[244:245], off sc1
	v_lshl_add_u64 v[242:243], v[136:137], 0, v[186:187]
	global_load_dwordx4 v[226:229], v[242:243], off sc1
	v_lshl_add_u64 v[244:245], v[136:137], 0, v[190:191]
	global_load_dwordx4 v[230:233], v[244:245], off sc1
	v_lshl_add_u64 v[242:243], v[136:137], 0, v[192:193]
	global_load_dwordx4 v[234:237], v[242:243], off sc1
	v_lshl_add_u64 v[244:245], v[136:137], 0, v[194:195]
	global_load_dwordx4 v[238:241], v[244:245], off sc1
	s_and_b64 vcc, exec, s[4:5]
	s_mov_b64 s[4:5], -1
	s_waitcnt vmcnt(0)
	v_add_f32_e32 v156, v208, v209
	v_add_f32_e32 v157, v210, v211
	s_nop 0
	v_add_f32_e32 v156, v156, v157
	ds_bpermute_b32 v157, v205, v156
	s_waitcnt lgkmcnt(0)
	v_add_f32_e32 v156, v156, v157
	ds_bpermute_b32 v157, v206, v156
	s_waitcnt lgkmcnt(0)
	v_add_f32_e32 v156, v156, v157
	v_fmamk_f32 v156, v156, 0x3a800000, v204
	v_rsq_f32_e32 v156, v156
	s_nop 0
	v_pk_mul_f32 v[124:125], v[124:125], v[156:157] op_sel_hi:[1,0]
	v_pk_mul_f32 v[126:127], v[126:127], v[156:157] op_sel_hi:[1,0]
	v_pk_mul_f32 v[120:121], v[120:121], v[156:157] op_sel_hi:[1,0]
	v_pk_mul_f32 v[122:123], v[122:123], v[156:157] op_sel_hi:[1,0]
	v_pk_mul_f32 v[208:209], v[116:117], v[156:157] op_sel_hi:[1,0]
	v_pk_mul_f32 v[210:211], v[118:119], v[156:157] op_sel_hi:[1,0]
	v_pk_mul_f32 v[212:213], v[112:113], v[156:157] op_sel_hi:[1,0]
	v_pk_mul_f32 v[156:157], v[114:115], v[156:157] op_sel_hi:[1,0]
	v_pk_mul_f32 v[114:115], v[14:15], v[126:127]
	v_pk_mul_f32 v[112:113], v[12:13], v[124:125]
	v_pk_mul_f32 v[118:119], v[6:7], v[122:123]
	v_pk_mul_f32 v[116:117], v[4:5], v[120:121]
	v_pk_mul_f32 v[122:123], v[10:11], v[210:211]
	v_pk_mul_f32 v[120:121], v[8:9], v[208:209]
	v_pk_mul_f32 v[126:127], v[2:3], v[156:157]
	v_pk_mul_f32 v[124:125], v[0:1], v[212:213]
	global_store_dwordx4 v[146:147], v[112:115], off nt
	global_store_dwordx4 v[146:147], v[116:119], off offset:16 nt
	global_store_dwordx4 v[146:147], v[120:123], off offset:512 nt
	global_store_dwordx4 v[146:147], v[124:127], off offset:528 nt
	v_add_f32_e32 v112, v214, v215
	v_add_f32_e32 v113, v216, v217
	s_nop 0
	v_add_f32_e32 v112, v112, v113
	ds_bpermute_b32 v113, v205, v112
	s_waitcnt lgkmcnt(0)
	v_add_f32_e32 v114, v112, v113
	ds_bpermute_b32 v115, v206, v114
	v_lshlrev_b64 v[112:113], 12, v[150:151]
	v_lshl_add_u64 v[112:113], s[8:9], 0, v[112:113]
	v_lshl_add_u64 v[112:113], v[112:113], 0, v[148:149]
	s_waitcnt lgkmcnt(0)
	v_add_f32_e32 v114, v114, v115
	v_fmamk_f32 v114, v114, 0x3a800000, v204
	v_rsq_f32_e32 v114, v114
	s_nop 0
	v_pk_mul_f32 v[108:109], v[108:109], v[114:115] op_sel_hi:[1,0]
	v_pk_mul_f32 v[110:111], v[110:111], v[114:115] op_sel_hi:[1,0]
	v_pk_mul_f32 v[104:105], v[104:105], v[114:115] op_sel_hi:[1,0]
	v_pk_mul_f32 v[106:107], v[106:107], v[114:115] op_sel_hi:[1,0]
	v_pk_mul_f32 v[118:119], v[100:101], v[114:115] op_sel_hi:[1,0]
	v_pk_mul_f32 v[120:121], v[102:103], v[114:115] op_sel_hi:[1,0]
	v_pk_mul_f32 v[122:123], v[96:97], v[114:115] op_sel_hi:[1,0]
	v_pk_mul_f32 v[114:115], v[98:99], v[114:115] op_sel_hi:[1,0]
	v_pk_mul_f32 v[98:99], v[14:15], v[110:111]
	v_pk_mul_f32 v[96:97], v[12:13], v[108:109]
	v_pk_mul_f32 v[102:103], v[6:7], v[106:107]
	v_pk_mul_f32 v[100:101], v[4:5], v[104:105]
	v_pk_mul_f32 v[106:107], v[10:11], v[120:121]
	v_pk_mul_f32 v[104:105], v[8:9], v[118:119]
	v_pk_mul_f32 v[110:111], v[2:3], v[114:115]
	v_pk_mul_f32 v[108:109], v[0:1], v[122:123]
	global_store_dwordx4 v[112:113], v[96:99], off nt
	global_store_dwordx4 v[112:113], v[100:103], off offset:16 nt
	global_store_dwordx4 v[112:113], v[104:107], off offset:512 nt
	global_store_dwordx4 v[112:113], v[108:111], off offset:528 nt
	v_add_f32_e32 v96, v218, v219
	v_add_f32_e32 v97, v220, v221
	s_nop 0
	v_add_f32_e32 v96, v96, v97
	ds_bpermute_b32 v97, v205, v96
	s_waitcnt lgkmcnt(0)
	v_add_f32_e32 v98, v96, v97
	ds_bpermute_b32 v99, v206, v98
	v_lshlrev_b64 v[96:97], 12, v[152:153]
	v_lshl_add_u64 v[96:97], s[8:9], 0, v[96:97]
	v_lshl_add_u64 v[96:97], v[96:97], 0, v[148:149]
	s_waitcnt lgkmcnt(0)
	v_add_f32_e32 v98, v98, v99
	v_fmamk_f32 v98, v98, 0x3a800000, v204
	v_rsq_f32_e32 v98, v98
	s_nop 0
	v_pk_mul_f32 v[92:93], v[92:93], v[98:99] op_sel_hi:[1,0]
	v_pk_mul_f32 v[94:95], v[94:95], v[98:99] op_sel_hi:[1,0]
	v_pk_mul_f32 v[88:89], v[88:89], v[98:99] op_sel_hi:[1,0]
	v_pk_mul_f32 v[90:91], v[90:91], v[98:99] op_sel_hi:[1,0]
	v_pk_mul_f32 v[102:103], v[84:85], v[98:99] op_sel_hi:[1,0]
	v_pk_mul_f32 v[104:105], v[86:87], v[98:99] op_sel_hi:[1,0]
	v_pk_mul_f32 v[106:107], v[80:81], v[98:99] op_sel_hi:[1,0]
	v_pk_mul_f32 v[98:99], v[82:83], v[98:99] op_sel_hi:[1,0]
	v_pk_mul_f32 v[82:83], v[14:15], v[94:95]
	v_pk_mul_f32 v[80:81], v[12:13], v[92:93]
	v_pk_mul_f32 v[86:87], v[6:7], v[90:91]
	v_pk_mul_f32 v[84:85], v[4:5], v[88:89]
	v_pk_mul_f32 v[90:91], v[10:11], v[104:105]
	v_pk_mul_f32 v[88:89], v[8:9], v[102:103]
	v_pk_mul_f32 v[94:95], v[2:3], v[98:99]
	v_pk_mul_f32 v[92:93], v[0:1], v[106:107]
	global_store_dwordx4 v[96:97], v[80:83], off nt
	global_store_dwordx4 v[96:97], v[84:87], off offset:16 nt
	global_store_dwordx4 v[96:97], v[88:91], off offset:512 nt
	global_store_dwordx4 v[96:97], v[92:95], off offset:528 nt
	v_add_f32_e32 v80, v222, v223
	v_add_f32_e32 v81, v224, v225
	s_nop 0
	v_add_f32_e32 v80, v80, v81
	ds_bpermute_b32 v81, v205, v80
	s_waitcnt lgkmcnt(0)
;     __device__ __forceinline__ void operator()(const f32x4 (&acc_)[2][2][4][2], const pg8::Unit& u, int wr, int wc, int fr, int fq) const {
;     ...
;             for (int m = 0; m < 4; ++m) {
;                 const int row = row0 + ai * 128 + m * 16; const float* xp = xch + (size_t)row * 16 + 4 * fq;
;                 float s = (__hip_atomic_load(xp + 0, __ATOMIC_RELAXED, __HIP_MEMORY_SCOPE_AGENT) + __hip_atomic_load(xp + 1, __ATOMIC_RELAXED, __HIP_MEMORY_SCOPE_AGENT))
;                         + (__hip_atomic_load(xp + 2, __ATOMIC_RELAXED, __HIP_MEMORY_SCOPE_AGENT) + __hip_atomic_load(xp + 3, __ATOMIC_RELAXED, __HIP_MEMORY_SCOPE_AGENT));
;                 s += __shfl_xor(s, 16); s += __shfl_xor(s, 32);
;                 const float rstd = __builtin_amdgcn_rsqf(s * (1.0f / 1024.0f) + EPS);
; #pragma unroll
;                 for (int bj = 0; bj < 2; ++bj) { const size_t off = (size_t)row * D + col0 + bj * 128;
;                     *(f32x4*)(out + off) = A[ai][bj][m][0] * rstd * g[bj][0]; *(f32x4*)(out + off + 4) = A[ai][bj][m][1] * rstd * g[bj][1]; }
;             }
	v_add_f32_e32 v82, v80, v81
	ds_bpermute_b32 v83, v206, v82
	v_lshlrev_b64 v[80:81], 12, v[154:155]
	v_lshl_add_u64 v[80:81], s[8:9], 0, v[80:81]
	v_lshl_add_u64 v[80:81], v[80:81], 0, v[148:149]
	s_waitcnt lgkmcnt(0)
	v_add_f32_e32 v82, v82, v83
	v_fmamk_f32 v82, v82, 0x3a800000, v204
	v_rsq_f32_e32 v82, v82
	s_nop 0
	v_pk_mul_f32 v[76:77], v[76:77], v[82:83] op_sel_hi:[1,0]
	v_pk_mul_f32 v[78:79], v[78:79], v[82:83] op_sel_hi:[1,0]
	v_pk_mul_f32 v[72:73], v[72:73], v[82:83] op_sel_hi:[1,0]
	v_pk_mul_f32 v[74:75], v[74:75], v[82:83] op_sel_hi:[1,0]
	v_pk_mul_f32 v[86:87], v[68:69], v[82:83] op_sel_hi:[1,0]
	v_pk_mul_f32 v[88:89], v[70:71], v[82:83] op_sel_hi:[1,0]
	v_pk_mul_f32 v[90:91], v[64:65], v[82:83] op_sel_hi:[1,0]
	v_pk_mul_f32 v[82:83], v[66:67], v[82:83] op_sel_hi:[1,0]
	v_pk_mul_f32 v[66:67], v[14:15], v[78:79]
	v_pk_mul_f32 v[64:65], v[12:13], v[76:77]
	v_pk_mul_f32 v[70:71], v[6:7], v[74:75]
	v_pk_mul_f32 v[68:69], v[4:5], v[72:73]
	v_pk_mul_f32 v[74:75], v[10:11], v[88:89]
	v_pk_mul_f32 v[72:73], v[8:9], v[86:87]
	v_pk_mul_f32 v[78:79], v[2:3], v[82:83]
	v_pk_mul_f32 v[76:77], v[0:1], v[90:91]
	global_store_dwordx4 v[80:81], v[64:67], off nt
	global_store_dwordx4 v[80:81], v[68:71], off offset:16 nt
	global_store_dwordx4 v[80:81], v[72:75], off offset:512 nt
	global_store_dwordx4 v[80:81], v[76:79], off offset:528 nt
	v_add_f32_e32 v64, v226, v227
	v_add_f32_e32 v65, v228, v229
	s_nop 0
	v_add_f32_e32 v64, v64, v65
	ds_bpermute_b32 v65, v205, v64
	s_waitcnt lgkmcnt(0)
	v_add_f32_e32 v66, v64, v65
	ds_bpermute_b32 v67, v206, v66
	v_lshlrev_b64 v[64:65], 12, v[158:159]
	v_lshl_add_u64 v[64:65], s[8:9], 0, v[64:65]
	v_lshl_add_u64 v[64:65], v[64:65], 0, v[148:149]
	s_waitcnt lgkmcnt(0)
	v_add_f32_e32 v66, v66, v67
	v_fmamk_f32 v66, v66, 0x3a800000, v204
	v_rsq_f32_e32 v66, v66
	s_nop 0
	v_pk_mul_f32 v[60:61], v[60:61], v[66:67] op_sel_hi:[1,0]
	v_pk_mul_f32 v[62:63], v[62:63], v[66:67] op_sel_hi:[1,0]
	v_pk_mul_f32 v[56:57], v[56:57], v[66:67] op_sel_hi:[1,0]
	v_pk_mul_f32 v[58:59], v[58:59], v[66:67] op_sel_hi:[1,0]
	v_pk_mul_f32 v[70:71], v[52:53], v[66:67] op_sel_hi:[1,0]
	v_pk_mul_f32 v[72:73], v[54:55], v[66:67] op_sel_hi:[1,0]
	v_pk_mul_f32 v[74:75], v[48:49], v[66:67] op_sel_hi:[1,0]
	v_pk_mul_f32 v[66:67], v[50:51], v[66:67] op_sel_hi:[1,0]
	v_pk_mul_f32 v[50:51], v[14:15], v[62:63]
	v_pk_mul_f32 v[48:49], v[12:13], v[60:61]
	v_pk_mul_f32 v[54:55], v[6:7], v[58:59]
	v_pk_mul_f32 v[52:53], v[4:5], v[56:57]
	v_pk_mul_f32 v[58:59], v[10:11], v[72:73]
	v_pk_mul_f32 v[56:57], v[8:9], v[70:71]
	v_pk_mul_f32 v[62:63], v[2:3], v[66:67]
	v_pk_mul_f32 v[60:61], v[0:1], v[74:75]
	global_store_dwordx4 v[64:65], v[48:51], off nt
	global_store_dwordx4 v[64:65], v[52:55], off offset:16 nt
	global_store_dwordx4 v[64:65], v[56:59], off offset:512 nt
	global_store_dwordx4 v[64:65], v[60:63], off offset:528 nt
	v_add_f32_e32 v48, v230, v231
	v_add_f32_e32 v49, v232, v233
	s_nop 0
	v_add_f32_e32 v48, v48, v49
	ds_bpermute_b32 v49, v205, v48
	s_waitcnt lgkmcnt(0)
	v_add_f32_e32 v50, v48, v49
	ds_bpermute_b32 v51, v206, v50
	v_lshlrev_b64 v[48:49], 12, v[162:163]
	v_lshl_add_u64 v[48:49], s[8:9], 0, v[48:49]
	v_lshl_add_u64 v[48:49], v[48:49], 0, v[148:149]
	s_waitcnt lgkmcnt(0)
;     __device__ __forceinline__ void operator()(const f32x4 (&acc_)[2][2][4][2], const pg8::Unit& u, int wr, int wc, int fr, int fq) const {
;     ...
; #pragma unroll
;         for (int ai = 0; ai < 2; ++ai)
; #pragma unroll
;             for (int m = 0; m < 4; ++m) {
;                 const int row = row0 + ai * 128 + m * 16; const float* xp = xch + (size_t)row * 16 + 4 * fq;
;                 float s = (__hip_atomic_load(xp + 0, __ATOMIC_RELAXED, __HIP_MEMORY_SCOPE_AGENT) + __hip_atomic_load(xp + 1, __ATOMIC_RELAXED, __HIP_MEMORY_SCOPE_AGENT))
;                         + (__hip_atomic_load(xp + 2, __ATOMIC_RELAXED, __HIP_MEMORY_SCOPE_AGENT) + __hip_atomic_load(xp + 3, __ATOMIC_RELAXED, __HIP_MEMORY_SCOPE_AGENT));
;                 s += __shfl_xor(s, 16); s += __shfl_xor(s, 32);
;                 const float rstd = __builtin_amdgcn_rsqf(s * (1.0f / 1024.0f) + EPS);
; #pragma unroll
;                 for (int bj = 0; bj < 2; ++bj) { const size_t off = (size_t)row * D + col0 + bj * 128;
;                     *(f32x4*)(out + off) = A[ai][bj][m][0] * rstd * g[bj][0]; *(f32x4*)(out + off + 4) = A[ai][bj][m][1] * rstd * g[bj][1]; }
;             }
	v_add_f32_e32 v50, v50, v51
	v_fmamk_f32 v50, v50, 0x3a800000, v204
	v_rsq_f32_e32 v50, v50
	s_nop 0
	v_pk_mul_f32 v[44:45], v[44:45], v[50:51] op_sel_hi:[1,0]
	v_pk_mul_f32 v[46:47], v[46:47], v[50:51] op_sel_hi:[1,0]
	v_pk_mul_f32 v[40:41], v[40:41], v[50:51] op_sel_hi:[1,0]
	v_pk_mul_f32 v[42:43], v[42:43], v[50:51] op_sel_hi:[1,0]
	v_pk_mul_f32 v[54:55], v[36:37], v[50:51] op_sel_hi:[1,0]
	v_pk_mul_f32 v[56:57], v[38:39], v[50:51] op_sel_hi:[1,0]
	v_pk_mul_f32 v[58:59], v[32:33], v[50:51] op_sel_hi:[1,0]
	v_pk_mul_f32 v[50:51], v[34:35], v[50:51] op_sel_hi:[1,0]
	v_pk_mul_f32 v[34:35], v[14:15], v[46:47]
	v_pk_mul_f32 v[32:33], v[12:13], v[44:45]
	v_pk_mul_f32 v[38:39], v[6:7], v[42:43]
	v_pk_mul_f32 v[36:37], v[4:5], v[40:41]
	v_pk_mul_f32 v[42:43], v[10:11], v[56:57]
	v_pk_mul_f32 v[40:41], v[8:9], v[54:55]
	v_pk_mul_f32 v[46:47], v[2:3], v[50:51]
	v_pk_mul_f32 v[44:45], v[0:1], v[58:59]
	global_store_dwordx4 v[48:49], v[32:35], off nt
	global_store_dwordx4 v[48:49], v[36:39], off offset:16 nt
	global_store_dwordx4 v[48:49], v[40:43], off offset:512 nt
	global_store_dwordx4 v[48:49], v[44:47], off offset:528 nt
	v_add_f32_e32 v32, v234, v235
	v_add_f32_e32 v33, v236, v237
	s_nop 0
	v_add_f32_e32 v32, v32, v33
	ds_bpermute_b32 v33, v205, v32
	s_waitcnt lgkmcnt(0)
	v_add_f32_e32 v34, v32, v33
	ds_bpermute_b32 v35, v206, v34
	v_lshlrev_b64 v[32:33], 12, v[166:167]
	v_lshl_add_u64 v[32:33], s[8:9], 0, v[32:33]
	v_lshl_add_u64 v[32:33], v[32:33], 0, v[148:149]
	s_waitcnt lgkmcnt(0)
	v_add_f32_e32 v34, v34, v35
	v_fmamk_f32 v34, v34, 0x3a800000, v204
	v_rsq_f32_e32 v34, v34
	s_nop 0
	v_pk_mul_f32 v[28:29], v[28:29], v[34:35] op_sel_hi:[1,0]
	v_pk_mul_f32 v[30:31], v[30:31], v[34:35] op_sel_hi:[1,0]
	v_pk_mul_f32 v[24:25], v[24:25], v[34:35] op_sel_hi:[1,0]
	v_pk_mul_f32 v[26:27], v[26:27], v[34:35] op_sel_hi:[1,0]
	v_pk_mul_f32 v[38:39], v[20:21], v[34:35] op_sel_hi:[1,0]
	v_pk_mul_f32 v[40:41], v[22:23], v[34:35] op_sel_hi:[1,0]
	v_pk_mul_f32 v[42:43], v[16:17], v[34:35] op_sel_hi:[1,0]
	v_pk_mul_f32 v[34:35], v[18:19], v[34:35] op_sel_hi:[1,0]
	v_pk_mul_f32 v[18:19], v[14:15], v[30:31]
	v_pk_mul_f32 v[16:17], v[12:13], v[28:29]
	v_pk_mul_f32 v[22:23], v[6:7], v[26:27]
	v_pk_mul_f32 v[20:21], v[4:5], v[24:25]
	v_pk_mul_f32 v[26:27], v[10:11], v[40:41]
	v_pk_mul_f32 v[24:25], v[8:9], v[38:39]
	v_pk_mul_f32 v[30:31], v[2:3], v[34:35]
	v_pk_mul_f32 v[28:29], v[0:1], v[42:43]
	global_store_dwordx4 v[32:33], v[16:19], off nt
	global_store_dwordx4 v[32:33], v[20:23], off offset:16 nt
	global_store_dwordx4 v[32:33], v[24:27], off offset:512 nt
	global_store_dwordx4 v[32:33], v[28:31], off offset:528 nt
	v_add_f32_e32 v16, v238, v239
	v_add_f32_e32 v17, v240, v241
	s_nop 0
	v_add_f32_e32 v16, v16, v17
	ds_bpermute_b32 v17, v205, v16
	s_waitcnt lgkmcnt(0)
	v_add_f32_e32 v18, v16, v17
	ds_bpermute_b32 v19, v206, v18
	v_lshlrev_b64 v[16:17], 12, v[170:171]
	v_lshl_add_u64 v[16:17], s[8:9], 0, v[16:17]
	v_lshl_add_u64 v[16:17], v[16:17], 0, v[148:149]
	s_waitcnt lgkmcnt(0)
	v_add_f32_e32 v18, v18, v19
	v_fmamk_f32 v18, v18, 0x3a800000, v204
	v_rsq_f32_e32 v18, v18
	s_nop 0
	v_pk_mul_f32 v[20:21], v[178:179], v[18:19] op_sel_hi:[1,0]
	v_pk_mul_f32 v[22:23], v[174:175], v[18:19] op_sel_hi:[1,0]
	v_pk_mul_f32 v[24:25], v[176:177], v[18:19] op_sel_hi:[1,0]
	v_pk_mul_f32 v[26:27], v[172:173], v[18:19] op_sel_hi:[1,0]
	v_pk_mul_f32 v[28:29], v[182:183], v[18:19] op_sel_hi:[1,0]
	v_pk_mul_f32 v[30:31], v[180:181], v[18:19] op_sel_hi:[1,0]
	v_pk_mul_f32 v[32:33], v[188:189], v[18:19] op_sel_hi:[1,0]
	v_pk_mul_f32 v[18:19], v[184:185], v[18:19] op_sel_hi:[1,0]
	v_pk_mul_f32 v[14:15], v[14:15], v[22:23]
	v_pk_mul_f32 v[12:13], v[12:13], v[20:21]
	v_pk_mul_f32 v[6:7], v[6:7], v[26:27]
	v_pk_mul_f32 v[4:5], v[4:5], v[24:25]
	v_pk_mul_f32 v[10:11], v[10:11], v[30:31]
	v_pk_mul_f32 v[8:9], v[8:9], v[28:29]
	v_pk_mul_f32 v[2:3], v[2:3], v[18:19]
	v_pk_mul_f32 v[0:1], v[0:1], v[32:33]
	global_store_dwordx4 v[16:17], v[12:15], off nt
	global_store_dwordx4 v[16:17], v[4:7], off offset:16 nt
	global_store_dwordx4 v[16:17], v[8:11], off offset:512 nt
	global_store_dwordx4 v[16:17], v[0:3], off offset:528 nt
	s_cbranch_vccnz .LBB0_948
	s_andn2_b64 vcc, exec, s[22:23]
	s_cbranch_vccnz .LBB0_947
	s_barrier
	s_branch .LBB0_947
